# branch hook: counted vmcnt waits at first consumer after the 16 ratio loads
# baseline (speedup 1.0000x reference)
; __device__ __forceinline__ void unpack8(const u32x4 w, float (&f)[8]) { f[0] = bflo(w.x); f[1] = bfhi(w.x); f[2] = bflo(w.y); f[3] = bfhi(w.y); f[4] = bflo(w.z); f[5] = bfhi(w.z); f[6] = bflo(w.w); f[7] = bfhi(w.w); }
;     __device__ __forceinline__ void segment(Acc& acc, const Unit& u, int seg, int wr, int wc, int fr, int fq) const {
;     ...
; #pragma unroll
;         for (int ai = 0; ai < 2; ++ai)
; #pragma unroll
;             for (int m = 0; m < 4; ++m)
; #pragma unroll
;                 for (int bj = 0; bj < 2; ++bj) rr[ai][m][bj] = *(const u32x4*)(rbase + ((ai * 4 + m) * 2 + bj) * 4096);
; #pragma unroll
;         for (int ai = 0; ai < 2; ++ai)
; #pragma unroll
;             for (int m = 0; m < 4; ++m)
; #pragma unroll
;                 for (int bj = 0; bj < 2; ++bj) { float r[8]; unpack8(rr[ai][m][bj], r);
; #pragma unroll
;                     for (int e = 0; e < 4; ++e) { acc[ai][bj][m][0][e] *= r[e]; acc[ai][bj][m][1][e] *= r[4 + e]; } }
.LBB0_131:
	s_cmp_eq_u32 s38, 0
	s_cselect_b64 s[42:43], -1, 0
	s_and_b32 s39, s38, 6
	s_cmp_lg_u32 s39, 0
	s_cselect_b64 s[96:97], -1, 0
	s_or_b64 s[42:43], s[42:43], s[96:97]
	s_and_b64 vcc, exec, s[42:43]
	s_cbranch_vccnz .LBB0_133
	s_lshr_b32 s39, s38, 3
	s_add_i32 s39, s39, -1
	s_mul_hi_i32 s43, s39, 0x4400000
	s_mul_i32 s39, s39, 0x4400000
	v_mov_b32_e32 v128, v181
	s_add_u32 s42, s11, s39
	s_addc_u32 s43, s13, s43
	v_ashrrev_i32_e32 v129, 31, v128
	v_lshl_add_u64 v[128:129], v[128:129], 1, s[42:43]
	global_load_dwordx4 v[184:187], v[128:129], off
	v_add_co_u32_e32 v130, vcc, s91, v128
	s_movk_i32 s39, 0x4000
	s_nop 0
	v_addc_co_u32_e32 v131, vcc, 0, v129, vcc
	global_load_dwordx4 v[210:213], v[130:131], off
	v_add_co_u32_e32 v130, vcc, s39, v128
	s_mov_b32 s39, 0x8000
	s_nop 0
	v_addc_co_u32_e32 v131, vcc, 0, v129, vcc
	v_add_co_u32_e32 v132, vcc, s52, v128
	s_nop 0
	s_nop 0
	v_addc_co_u32_e32 v133, vcc, 0, v129, vcc
	global_load_dwordx4 v[214:217], v[130:131], off
	global_load_dwordx4 v[218:221], v[132:133], off
	v_add_co_u32_e32 v130, vcc, s39, v128
	s_mov_b32 s39, 0xa000
	s_nop 0
	v_addc_co_u32_e32 v131, vcc, 0, v129, vcc
	v_add_co_u32_e32 v132, vcc, s39, v128
	s_mov_b32 s39, 0xc000
	s_nop 0
	v_addc_co_u32_e32 v133, vcc, 0, v129, vcc
	global_load_dwordx4 v[222:225], v[130:131], off
	global_load_dwordx4 v[226:229], v[132:133], off
	v_add_co_u32_e32 v130, vcc, s39, v128
	s_mov_b32 s39, 0x10000
	s_nop 0
	v_addc_co_u32_e32 v131, vcc, 0, v129, vcc
	v_add_co_u32_e32 v132, vcc, s29, v128
	s_nop 0
	s_nop 0
	v_addc_co_u32_e32 v133, vcc, 0, v129, vcc
	global_load_dwordx4 v[230:233], v[130:131], off
	global_load_dwordx4 v[234:237], v[132:133], off
	v_add_co_u32_e32 v130, vcc, s39, v128
	s_mov_b32 s39, 0x12000
	s_nop 0
	v_addc_co_u32_e32 v131, vcc, 0, v129, vcc
	v_add_co_u32_e32 v132, vcc, s39, v128
	s_mov_b32 s39, 0x14000
	s_nop 0
	v_addc_co_u32_e32 v133, vcc, 0, v129, vcc
	global_load_dwordx4 v[156:159], v[130:131], off
	global_load_dwordx4 v[152:155], v[132:133], off
	v_add_co_u32_e32 v130, vcc, s39, v128
	s_mov_b32 s39, 0x16000
	s_nop 0
	v_addc_co_u32_e32 v131, vcc, 0, v129, vcc
	v_add_co_u32_e32 v132, vcc, s39, v128
	s_mov_b32 s39, 0x18000
	s_nop 0
	v_addc_co_u32_e32 v133, vcc, 0, v129, vcc
	global_load_dwordx4 v[148:151], v[130:131], off
	global_load_dwordx4 v[144:147], v[132:133], off
	v_add_co_u32_e32 v130, vcc, s39, v128
	s_mov_b32 s39, 0x1a000
	s_nop 0
	v_addc_co_u32_e32 v131, vcc, 0, v129, vcc
	v_add_co_u32_e32 v132, vcc, s39, v128
	s_mov_b32 s39, 0x1c000
	s_nop 0
	v_addc_co_u32_e32 v133, vcc, 0, v129, vcc
	global_load_dwordx4 v[140:143], v[130:131], off
	global_load_dwordx4 v[136:139], v[132:133], off
	v_add_co_u32_e32 v130, vcc, s39, v128
	s_mov_b32 s39, 0x1e000
	s_nop 0
	v_addc_co_u32_e32 v131, vcc, 0, v129, vcc
	v_add_co_u32_e32 v128, vcc, s39, v128
	s_nop 0
	s_nop 0
	v_addc_co_u32_e32 v129, vcc, 0, v129, vcc
	global_load_dwordx4 v[132:135], v[130:131], off
	s_nop 0
	global_load_dwordx4 v[128:131], v[128:129], off
	s_waitcnt vmcnt(15)
	v_lshlrev_b32_e32 v188, 16, v184
	v_and_b32_e32 v189, 0xffff0000, v184
	v_lshlrev_b32_e32 v184, 16, v185
	v_and_b32_e32 v185, 0xffff0000, v185
	v_pk_mul_f32 v[122:123], v[122:123], v[184:185]
	v_lshlrev_b32_e32 v184, 16, v187
	v_and_b32_e32 v185, 0xffff0000, v187
	v_pk_mul_f32 v[126:127], v[126:127], v[184:185]
	s_waitcnt vmcnt(14)
	v_lshlrev_b32_e32 v184, 16, v210
	v_and_b32_e32 v185, 0xffff0000, v210
	v_pk_mul_f32 v[116:117], v[116:117], v[184:185]
	v_lshlrev_b32_e32 v184, 16, v212
	v_and_b32_e32 v185, 0xffff0000, v212
	v_pk_mul_f32 v[112:113], v[112:113], v[184:185]
	v_lshlrev_b32_e32 v184, 16, v211
	v_and_b32_e32 v185, 0xffff0000, v211
	v_pk_mul_f32 v[118:119], v[118:119], v[184:185]
	v_lshlrev_b32_e32 v184, 16, v213
	v_and_b32_e32 v185, 0xffff0000, v213
	v_pk_mul_f32 v[114:115], v[114:115], v[184:185]
	s_waitcnt vmcnt(13)
	v_lshlrev_b32_e32 v184, 16, v214
	v_and_b32_e32 v185, 0xffff0000, v214
	v_pk_mul_f32 v[108:109], v[108:109], v[184:185]
	v_lshlrev_b32_e32 v184, 16, v216
	v_and_b32_e32 v185, 0xffff0000, v216
	v_pk_mul_f32 v[104:105], v[104:105], v[184:185]
	v_lshlrev_b32_e32 v184, 16, v215
	v_and_b32_e32 v185, 0xffff0000, v215
	v_pk_mul_f32 v[110:111], v[110:111], v[184:185]
	v_lshlrev_b32_e32 v184, 16, v217
	v_and_b32_e32 v185, 0xffff0000, v217
	v_pk_mul_f32 v[106:107], v[106:107], v[184:185]
	s_waitcnt vmcnt(12)
	v_lshlrev_b32_e32 v184, 16, v218
	v_and_b32_e32 v185, 0xffff0000, v218
	v_pk_mul_f32 v[100:101], v[100:101], v[184:185]
	v_lshlrev_b32_e32 v184, 16, v220
	v_and_b32_e32 v185, 0xffff0000, v220
	v_pk_mul_f32 v[96:97], v[96:97], v[184:185]
	v_lshlrev_b32_e32 v184, 16, v219
	v_and_b32_e32 v185, 0xffff0000, v219
	v_pk_mul_f32 v[102:103], v[102:103], v[184:185]
	v_lshlrev_b32_e32 v184, 16, v221
	v_and_b32_e32 v185, 0xffff0000, v221
	v_pk_mul_f32 v[98:99], v[98:99], v[184:185]
	s_waitcnt vmcnt(11)
	v_lshlrev_b32_e32 v184, 16, v222
	v_and_b32_e32 v185, 0xffff0000, v222
	v_pk_mul_f32 v[92:93], v[92:93], v[184:185]
	v_lshlrev_b32_e32 v184, 16, v224
	v_and_b32_e32 v185, 0xffff0000, v224
	v_pk_mul_f32 v[88:89], v[88:89], v[184:185]
	v_lshlrev_b32_e32 v184, 16, v223
	v_and_b32_e32 v185, 0xffff0000, v223
	v_pk_mul_f32 v[94:95], v[94:95], v[184:185]
	v_lshlrev_b32_e32 v184, 16, v225
	v_and_b32_e32 v185, 0xffff0000, v225
	v_pk_mul_f32 v[90:91], v[90:91], v[184:185]
	s_waitcnt vmcnt(10)
; __device__ __forceinline__ void unpack8(const u32x4 w, float (&f)[8]) { f[0] = bflo(w.x); f[1] = bfhi(w.x); f[2] = bflo(w.y); f[3] = bfhi(w.y); f[4] = bflo(w.z); f[5] = bfhi(w.z); f[6] = bflo(w.w); f[7] = bfhi(w.w); }
;     __device__ __forceinline__ void segment(Acc& acc, const Unit& u, int seg, int wr, int wc, int fr, int fq) const {
;     ...
; #pragma unroll
;         for (int ai = 0; ai < 2; ++ai)
; #pragma unroll
;             for (int m = 0; m < 4; ++m)
; #pragma unroll
;                 for (int bj = 0; bj < 2; ++bj) rr[ai][m][bj] = *(const u32x4*)(rbase + ((ai * 4 + m) * 2 + bj) * 4096);
; #pragma unroll
;         for (int ai = 0; ai < 2; ++ai)
; #pragma unroll
;             for (int m = 0; m < 4; ++m)
; #pragma unroll
;                 for (int bj = 0; bj < 2; ++bj) { float r[8]; unpack8(rr[ai][m][bj], r);
; #pragma unroll
;                     for (int e = 0; e < 4; ++e) { acc[ai][bj][m][0][e] *= r[e]; acc[ai][bj][m][1][e] *= r[4 + e]; } }
	v_lshlrev_b32_e32 v184, 16, v226
	v_and_b32_e32 v185, 0xffff0000, v226
	v_pk_mul_f32 v[84:85], v[84:85], v[184:185]
	v_lshlrev_b32_e32 v184, 16, v228
	v_and_b32_e32 v185, 0xffff0000, v228
	v_pk_mul_f32 v[80:81], v[80:81], v[184:185]
	v_lshlrev_b32_e32 v184, 16, v227
	v_and_b32_e32 v185, 0xffff0000, v227
	v_pk_mul_f32 v[86:87], v[86:87], v[184:185]
	v_lshlrev_b32_e32 v184, 16, v229
	v_and_b32_e32 v185, 0xffff0000, v229
	v_pk_mul_f32 v[82:83], v[82:83], v[184:185]
	s_waitcnt vmcnt(9)
	v_lshlrev_b32_e32 v184, 16, v230
	v_and_b32_e32 v185, 0xffff0000, v230
	v_pk_mul_f32 v[76:77], v[76:77], v[184:185]
	v_lshlrev_b32_e32 v184, 16, v232
	v_and_b32_e32 v185, 0xffff0000, v232
	v_pk_mul_f32 v[72:73], v[72:73], v[184:185]
	v_lshlrev_b32_e32 v184, 16, v231
	v_and_b32_e32 v185, 0xffff0000, v231
	v_pk_mul_f32 v[78:79], v[78:79], v[184:185]
	v_lshlrev_b32_e32 v184, 16, v233
	v_and_b32_e32 v185, 0xffff0000, v233
	v_pk_mul_f32 v[74:75], v[74:75], v[184:185]
	s_waitcnt vmcnt(8)
	v_lshlrev_b32_e32 v184, 16, v234
	v_and_b32_e32 v185, 0xffff0000, v234
	v_pk_mul_f32 v[68:69], v[68:69], v[184:185]
	v_lshlrev_b32_e32 v184, 16, v236
	v_and_b32_e32 v185, 0xffff0000, v236
	v_pk_mul_f32 v[64:65], v[64:65], v[184:185]
	v_lshlrev_b32_e32 v184, 16, v235
	v_and_b32_e32 v185, 0xffff0000, v235
	v_pk_mul_f32 v[70:71], v[70:71], v[184:185]
	v_lshlrev_b32_e32 v184, 16, v237
	v_and_b32_e32 v185, 0xffff0000, v237
	v_pk_mul_f32 v[66:67], v[66:67], v[184:185]
	s_waitcnt vmcnt(7)
	v_lshlrev_b32_e32 v184, 16, v156
	v_and_b32_e32 v185, 0xffff0000, v156
	v_lshlrev_b32_e32 v156, 16, v157
	v_and_b32_e32 v157, 0xffff0000, v157
	v_pk_mul_f32 v[62:63], v[62:63], v[156:157]
	v_lshlrev_b32_e32 v156, 16, v159
	v_and_b32_e32 v157, 0xffff0000, v159
	v_pk_mul_f32 v[58:59], v[58:59], v[156:157]
	s_waitcnt vmcnt(6)
	v_lshlrev_b32_e32 v156, 16, v152
	v_and_b32_e32 v157, 0xffff0000, v152
	v_lshlrev_b32_e32 v152, 16, v153
	v_and_b32_e32 v153, 0xffff0000, v153
	v_pk_mul_f32 v[54:55], v[54:55], v[152:153]
	v_lshlrev_b32_e32 v152, 16, v155
	v_and_b32_e32 v153, 0xffff0000, v155
	v_pk_mul_f32 v[50:51], v[50:51], v[152:153]
	s_waitcnt vmcnt(5)
	v_lshlrev_b32_e32 v152, 16, v148
	v_and_b32_e32 v153, 0xffff0000, v148
	v_lshlrev_b32_e32 v148, 16, v149
	v_and_b32_e32 v149, 0xffff0000, v149
	v_pk_mul_f32 v[46:47], v[46:47], v[148:149]
	v_lshlrev_b32_e32 v148, 16, v151
	v_and_b32_e32 v149, 0xffff0000, v151
	v_pk_mul_f32 v[42:43], v[42:43], v[148:149]
	s_waitcnt vmcnt(4)
	v_lshlrev_b32_e32 v148, 16, v144
	v_and_b32_e32 v149, 0xffff0000, v144
	v_lshlrev_b32_e32 v144, 16, v145
	v_and_b32_e32 v145, 0xffff0000, v145
	v_pk_mul_f32 v[38:39], v[38:39], v[144:145]
	v_lshlrev_b32_e32 v144, 16, v147
	v_and_b32_e32 v145, 0xffff0000, v147
	v_pk_mul_f32 v[34:35], v[34:35], v[144:145]
	s_waitcnt vmcnt(3)
	v_lshlrev_b32_e32 v144, 16, v140
	v_and_b32_e32 v145, 0xffff0000, v140
	v_lshlrev_b32_e32 v140, 16, v141
	v_and_b32_e32 v141, 0xffff0000, v141
	v_pk_mul_f32 v[30:31], v[30:31], v[140:141]
	v_lshlrev_b32_e32 v140, 16, v143
	v_and_b32_e32 v141, 0xffff0000, v143
	v_pk_mul_f32 v[26:27], v[26:27], v[140:141]
	s_waitcnt vmcnt(2)
	v_lshlrev_b32_e32 v140, 16, v136
	v_and_b32_e32 v141, 0xffff0000, v136
	v_lshlrev_b32_e32 v136, 16, v137
	v_and_b32_e32 v137, 0xffff0000, v137
	v_pk_mul_f32 v[22:23], v[22:23], v[136:137]
	v_lshlrev_b32_e32 v136, 16, v139
	v_and_b32_e32 v137, 0xffff0000, v139
	v_pk_mul_f32 v[18:19], v[18:19], v[136:137]
	s_waitcnt vmcnt(1)
	v_lshlrev_b32_e32 v136, 16, v132
	v_and_b32_e32 v137, 0xffff0000, v132
	v_lshlrev_b32_e32 v132, 16, v133
	v_and_b32_e32 v133, 0xffff0000, v133
	v_pk_mul_f32 v[14:15], v[14:15], v[132:133]
	v_lshlrev_b32_e32 v132, 16, v135
	v_and_b32_e32 v133, 0xffff0000, v135
	v_pk_mul_f32 v[10:11], v[10:11], v[132:133]
	s_waitcnt vmcnt(0)
	v_lshlrev_b32_e32 v132, 16, v128
	v_and_b32_e32 v133, 0xffff0000, v128
	v_lshlrev_b32_e32 v128, 16, v129
	v_and_b32_e32 v129, 0xffff0000, v129
	v_pk_mul_f32 v[120:121], v[120:121], v[188:189]
	v_lshlrev_b32_e32 v188, 16, v186
	v_and_b32_e32 v189, 0xffff0000, v186
	v_pk_mul_f32 v[60:61], v[60:61], v[184:185]
	v_lshlrev_b32_e32 v184, 16, v158
	v_and_b32_e32 v185, 0xffff0000, v158
	v_pk_mul_f32 v[52:53], v[52:53], v[156:157]
	v_lshlrev_b32_e32 v156, 16, v154
	v_and_b32_e32 v157, 0xffff0000, v154
	v_pk_mul_f32 v[44:45], v[44:45], v[152:153]
	v_lshlrev_b32_e32 v152, 16, v150
	v_and_b32_e32 v153, 0xffff0000, v150
	v_pk_mul_f32 v[36:37], v[36:37], v[148:149]
	v_lshlrev_b32_e32 v148, 16, v146
	v_and_b32_e32 v149, 0xffff0000, v146
	v_pk_mul_f32 v[28:29], v[28:29], v[144:145]
	v_lshlrev_b32_e32 v144, 16, v142
	v_and_b32_e32 v145, 0xffff0000, v142
	v_pk_mul_f32 v[20:21], v[20:21], v[140:141]
	v_lshlrev_b32_e32 v140, 16, v138
	v_and_b32_e32 v141, 0xffff0000, v138
	v_pk_mul_f32 v[12:13], v[12:13], v[136:137]
	v_lshlrev_b32_e32 v136, 16, v134
	v_and_b32_e32 v137, 0xffff0000, v134
	v_pk_mul_f32 v[4:5], v[4:5], v[132:133]
	v_lshlrev_b32_e32 v132, 16, v130
	v_and_b32_e32 v133, 0xffff0000, v130
	v_pk_mul_f32 v[6:7], v[6:7], v[128:129]
	v_lshlrev_b32_e32 v128, 16, v131
	v_and_b32_e32 v129, 0xffff0000, v131
	v_pk_mul_f32 v[124:125], v[124:125], v[188:189]
	v_pk_mul_f32 v[56:57], v[56:57], v[184:185]
	v_pk_mul_f32 v[48:49], v[48:49], v[156:157]
	v_pk_mul_f32 v[40:41], v[40:41], v[152:153]
	v_pk_mul_f32 v[32:33], v[32:33], v[148:149]
	v_pk_mul_f32 v[24:25], v[24:25], v[144:145]
	v_pk_mul_f32 v[16:17], v[16:17], v[140:141]
	v_pk_mul_f32 v[8:9], v[8:9], v[136:137]
	v_pk_mul_f32 v[0:1], v[0:1], v[132:133]
	v_pk_mul_f32 v[2:3], v[2:3], v[128:129]
